# w_in/mlp_in GEMM epilogues run in the loop's own stagger (each wave half stores while the other half does its MFMA phase) instead of re-aligning the halves around the epilogue
# baseline (speedup 1.0000x reference)
; __device__ __forceinline__ unsigned cvt_pk_bf16(float lo, float hi) { const f32x2 v = (f32x2){lo, hi}; return __builtin_bit_cast(unsigned, __builtin_convertvector(v, bf16v2)); }
; #define PG8_BAR __builtin_amdgcn_s_barrier()
;     __device__ __forceinline__ void operator()(f32x4 (&acc)[2][2][4][2], const Unit& u, int wr, int wc, int fr, int fq, LAS unsigned char* xl, int wid, int lane) const {
;     ...
; #pragma unroll
;         for (int ai = 0; ai < 2; ++ai)
; #pragma unroll
;             for (int m = 0; m < 4; ++m) { bf16_t* rowp = base + (size_t)(row0 + ai * HALF + m * 16) * ldc + col0;
; #pragma unroll
;                 for (int bj = 0; bj < 2; ++bj) { f32x4 v0 = acc[ai][bj][m][0], v1 = acc[ai][bj][m][1];
;                     if (MODE == 2) {
; #pragma unroll
;                         for (int e = 0; e < 4; ++e) { const float a = fmaxf(v0[e], 0.f), b = fmaxf(v1[e], 0.f); v0[e] = a * a; v1[e] = b * b; } }
;                     u32x4 w; w.x = cvt_pk_bf16(v0[0], v0[1]); w.y = cvt_pk_bf16(v0[2], v0[3]); w.z = cvt_pk_bf16(v1[0], v1[1]); w.w = cvt_pk_bf16(v1[2], v1[3]);
;                     *(u32x4*)(rowp + bj * HALF) = w; } }
; template <class EpiT, bool ALIGN_EPI>
; __device__ __forceinline__ void gemm_phase(LAS unsigned char* lds, const Gemm g, const StaticOrder& S, const EpiT& E, const int tid) {
;     ...
;         if constexpr (ALIGN_EPI) { if (wr == 0) PG8_BAR; }
.LBB0_186:
	v_max_f32_e32 v120, v120, v120
	v_max_f32_e32 v121, v121, v121
	v_max_f32_e32 v120, 0, v120
	v_max_f32_e32 v121, 0, v121
	v_pk_mul_f32 v[148:149], v[120:121], v[120:121]
	v_max_f32_e32 v121, v122, v122
	v_lshl_add_u32 v144, s20, 8, v140
	v_lshl_or_b32 v138, s69, 8, v142
	v_max_f32_e32 v124, v124, v124
	v_max_f32_e32 v125, v125, v125
	v_max_f32_e32 v120, v126, v126
	v_max_f32_e32 v122, 0, v121
	v_max_f32_e32 v121, v127, v127
	v_max_f32_e32 v123, v123, v123
	v_ashrrev_i32_e32 v139, 31, v138
	v_ashrrev_i32_e32 v145, 31, v144
	v_max_f32_e32 v124, 0, v124
	v_max_f32_e32 v125, 0, v125
	v_max_f32_e32 v120, 0, v120
	v_max_f32_e32 v121, 0, v121
	v_max_f32_e32 v123, 0, v123
	v_lshl_add_u64 v[146:147], v[138:139], 1, s[8:9]
	v_lshlrev_b64 v[138:139], 13, v[144:145]
	v_pk_mul_f32 v[124:125], v[124:125], v[124:125]
	v_pk_mul_f32 v[126:127], v[120:121], v[120:121]
	v_pk_mul_f32 v[150:151], v[122:123], v[122:123]
	v_max_f32_e32 v112, v112, v112
	v_max_f32_e32 v113, v113, v113
	v_lshl_add_u64 v[138:139], v[146:147], 0, v[138:139]
	v_cvt_pk_bf16_f32 v120, v124, v125
	v_cvt_pk_bf16_f32 v121, v126, v127
	v_cvt_pk_bf16_f32 v122, v148, v149
	v_cvt_pk_bf16_f32 v123, v150, v151
	v_max_f32_e32 v112, 0, v112
	v_max_f32_e32 v113, 0, v113
	global_store_dwordx4 v[138:139], v[120:123], off
	v_max_f32_e32 v116, v116, v116
	v_max_f32_e32 v117, v117, v117
	v_pk_mul_f32 v[120:121], v[112:113], v[112:113]
	v_max_f32_e32 v113, v114, v114
	v_max_f32_e32 v112, v118, v118
	v_max_f32_e32 v114, 0, v113
	v_max_f32_e32 v113, v119, v119
	v_max_f32_e32 v115, v115, v115
	v_max_f32_e32 v116, 0, v116
	v_max_f32_e32 v117, 0, v117
	v_max_f32_e32 v112, 0, v112
	v_max_f32_e32 v113, 0, v113
	v_max_f32_e32 v115, 0, v115
	v_pk_mul_f32 v[116:117], v[116:117], v[116:117]
	v_pk_mul_f32 v[118:119], v[112:113], v[112:113]
	v_pk_mul_f32 v[122:123], v[114:115], v[114:115]
	v_max_f32_e32 v104, v104, v104
	v_max_f32_e32 v105, v105, v105
	v_cvt_pk_bf16_f32 v112, v116, v117
	v_cvt_pk_bf16_f32 v113, v118, v119
	v_cvt_pk_bf16_f32 v114, v120, v121
	v_cvt_pk_bf16_f32 v115, v122, v123
	v_max_f32_e32 v104, 0, v104
	v_max_f32_e32 v105, 0, v105
	global_store_dwordx4 v[138:139], v[112:115], off offset:256
	v_max_f32_e32 v108, v108, v108
	v_max_f32_e32 v109, v109, v109
	v_pk_mul_f32 v[114:115], v[104:105], v[104:105]
	v_max_f32_e32 v105, v106, v106
	v_or_b32_e32 v112, 16, v144
	v_max_f32_e32 v104, v110, v110
	v_max_f32_e32 v106, 0, v105
	v_max_f32_e32 v105, v111, v111
	v_max_f32_e32 v107, v107, v107
	v_ashrrev_i32_e32 v113, 31, v112
	v_max_f32_e32 v108, 0, v108
	v_max_f32_e32 v109, 0, v109
	v_max_f32_e32 v104, 0, v104
	v_max_f32_e32 v105, 0, v105
	v_max_f32_e32 v107, 0, v107
	v_lshlrev_b64 v[112:113], 13, v[112:113]
	v_pk_mul_f32 v[108:109], v[108:109], v[108:109]
	v_pk_mul_f32 v[110:111], v[104:105], v[104:105]
	v_pk_mul_f32 v[116:117], v[106:107], v[106:107]
	v_max_f32_e32 v96, v96, v96
	v_max_f32_e32 v97, v97, v97
	v_lshl_add_u64 v[112:113], v[146:147], 0, v[112:113]
	v_cvt_pk_bf16_f32 v104, v108, v109
	v_cvt_pk_bf16_f32 v105, v110, v111
	v_cvt_pk_bf16_f32 v106, v114, v115
	v_cvt_pk_bf16_f32 v107, v116, v117
	v_max_f32_e32 v96, 0, v96
	v_max_f32_e32 v97, 0, v97
	global_store_dwordx4 v[112:113], v[104:107], off
	v_max_f32_e32 v100, v100, v100
	v_max_f32_e32 v101, v101, v101
	v_pk_mul_f32 v[104:105], v[96:97], v[96:97]
	v_max_f32_e32 v97, v98, v98
	v_max_f32_e32 v96, v102, v102
	v_max_f32_e32 v98, 0, v97
	v_max_f32_e32 v97, v103, v103
	v_max_f32_e32 v99, v99, v99
	v_max_f32_e32 v100, 0, v100
	v_max_f32_e32 v101, 0, v101
	v_max_f32_e32 v96, 0, v96
	v_max_f32_e32 v97, 0, v97
	v_max_f32_e32 v99, 0, v99
	v_pk_mul_f32 v[100:101], v[100:101], v[100:101]
	v_pk_mul_f32 v[102:103], v[96:97], v[96:97]
	v_pk_mul_f32 v[106:107], v[98:99], v[98:99]
	v_max_f32_e32 v88, v88, v88
	v_max_f32_e32 v89, v89, v89
	v_cvt_pk_bf16_f32 v96, v100, v101
	v_cvt_pk_bf16_f32 v97, v102, v103
	v_cvt_pk_bf16_f32 v98, v104, v105
	v_cvt_pk_bf16_f32 v99, v106, v107
	v_max_f32_e32 v88, 0, v88
	v_max_f32_e32 v89, 0, v89
	global_store_dwordx4 v[112:113], v[96:99], off offset:256
	v_max_f32_e32 v92, v92, v92
	v_max_f32_e32 v93, v93, v93
	v_pk_mul_f32 v[98:99], v[88:89], v[88:89]
	v_max_f32_e32 v89, v90, v90
	v_or_b32_e32 v96, 32, v144
	v_max_f32_e32 v88, v94, v94
	v_max_f32_e32 v90, 0, v89
	v_max_f32_e32 v89, v95, v95
	v_max_f32_e32 v91, v91, v91
	v_ashrrev_i32_e32 v97, 31, v96
	v_max_f32_e32 v92, 0, v92
	v_max_f32_e32 v93, 0, v93
	v_max_f32_e32 v88, 0, v88
	v_max_f32_e32 v89, 0, v89
	v_max_f32_e32 v91, 0, v91
	v_lshlrev_b64 v[96:97], 13, v[96:97]
	v_pk_mul_f32 v[92:93], v[92:93], v[92:93]
	v_pk_mul_f32 v[94:95], v[88:89], v[88:89]
	v_pk_mul_f32 v[100:101], v[90:91], v[90:91]
	v_max_f32_e32 v80, v80, v80
	v_max_f32_e32 v81, v81, v81
	v_lshl_add_u64 v[96:97], v[146:147], 0, v[96:97]
	v_cvt_pk_bf16_f32 v88, v92, v93
	v_cvt_pk_bf16_f32 v89, v94, v95
	v_cvt_pk_bf16_f32 v90, v98, v99
	v_cvt_pk_bf16_f32 v91, v100, v101
	v_max_f32_e32 v80, 0, v80
	v_max_f32_e32 v81, 0, v81
	global_store_dwordx4 v[96:97], v[88:91], off
	v_max_f32_e32 v84, v84, v84
	v_max_f32_e32 v85, v85, v85
	v_pk_mul_f32 v[88:89], v[80:81], v[80:81]
	v_max_f32_e32 v81, v82, v82
	v_max_f32_e32 v80, v86, v86
	v_max_f32_e32 v82, 0, v81
	v_max_f32_e32 v81, v87, v87
	v_max_f32_e32 v83, v83, v83
	v_max_f32_e32 v84, 0, v84
	v_max_f32_e32 v85, 0, v85
	v_max_f32_e32 v80, 0, v80
	v_max_f32_e32 v81, 0, v81
	v_max_f32_e32 v83, 0, v83
	v_pk_mul_f32 v[84:85], v[84:85], v[84:85]
	v_pk_mul_f32 v[86:87], v[80:81], v[80:81]
	v_pk_mul_f32 v[90:91], v[82:83], v[82:83]
	v_max_f32_e32 v72, v72, v72
	v_max_f32_e32 v73, v73, v73
	v_cvt_pk_bf16_f32 v80, v84, v85
	v_cvt_pk_bf16_f32 v81, v86, v87
; __device__ __forceinline__ unsigned cvt_pk_bf16(float lo, float hi) { const f32x2 v = (f32x2){lo, hi}; return __builtin_bit_cast(unsigned, __builtin_convertvector(v, bf16v2)); }
;     __device__ __forceinline__ void operator()(f32x4 (&acc)[2][2][4][2], const Unit& u, int wr, int wc, int fr, int fq, LAS unsigned char* xl, int wid, int lane) const {
;     ...
; #pragma unroll
;         for (int ai = 0; ai < 2; ++ai)
; #pragma unroll
;             for (int m = 0; m < 4; ++m) { bf16_t* rowp = base + (size_t)(row0 + ai * HALF + m * 16) * ldc + col0;
; #pragma unroll
;                 for (int bj = 0; bj < 2; ++bj) { f32x4 v0 = acc[ai][bj][m][0], v1 = acc[ai][bj][m][1];
;                     if (MODE == 2) {
; #pragma unroll
;                         for (int e = 0; e < 4; ++e) { const float a = fmaxf(v0[e], 0.f), b = fmaxf(v1[e], 0.f); v0[e] = a * a; v1[e] = b * b; } }
;                     u32x4 w; w.x = cvt_pk_bf16(v0[0], v0[1]); w.y = cvt_pk_bf16(v0[2], v0[3]); w.z = cvt_pk_bf16(v1[0], v1[1]); w.w = cvt_pk_bf16(v1[2], v1[3]);
;                     *(u32x4*)(rowp + bj * HALF) = w; } }
	v_cvt_pk_bf16_f32 v82, v88, v89
	v_cvt_pk_bf16_f32 v83, v90, v91
	v_max_f32_e32 v72, 0, v72
	v_max_f32_e32 v73, 0, v73
	global_store_dwordx4 v[96:97], v[80:83], off offset:256
	v_max_f32_e32 v76, v76, v76
	v_max_f32_e32 v77, v77, v77
	v_pk_mul_f32 v[82:83], v[72:73], v[72:73]
	v_max_f32_e32 v73, v74, v74
	v_or_b32_e32 v80, 48, v144
	v_max_f32_e32 v72, v78, v78
	v_max_f32_e32 v74, 0, v73
	v_max_f32_e32 v73, v79, v79
	v_max_f32_e32 v75, v75, v75
	v_ashrrev_i32_e32 v81, 31, v80
	v_max_f32_e32 v76, 0, v76
	v_max_f32_e32 v77, 0, v77
	v_max_f32_e32 v72, 0, v72
	v_max_f32_e32 v73, 0, v73
	v_max_f32_e32 v75, 0, v75
	v_lshlrev_b64 v[80:81], 13, v[80:81]
	v_pk_mul_f32 v[76:77], v[76:77], v[76:77]
	v_pk_mul_f32 v[78:79], v[72:73], v[72:73]
	v_pk_mul_f32 v[84:85], v[74:75], v[74:75]
	v_max_f32_e32 v64, v64, v64
	v_max_f32_e32 v65, v65, v65
	v_lshl_add_u64 v[80:81], v[146:147], 0, v[80:81]
	v_cvt_pk_bf16_f32 v72, v76, v77
	v_cvt_pk_bf16_f32 v73, v78, v79
	v_cvt_pk_bf16_f32 v74, v82, v83
	v_cvt_pk_bf16_f32 v75, v84, v85
	v_max_f32_e32 v64, 0, v64
	v_max_f32_e32 v65, 0, v65
	global_store_dwordx4 v[80:81], v[72:75], off
	v_max_f32_e32 v68, v68, v68
	v_max_f32_e32 v69, v69, v69
	v_pk_mul_f32 v[72:73], v[64:65], v[64:65]
	v_max_f32_e32 v65, v66, v66
	v_max_f32_e32 v64, v70, v70
	v_max_f32_e32 v66, 0, v65
	v_max_f32_e32 v65, v71, v71
	v_max_f32_e32 v67, v67, v67
	v_max_f32_e32 v68, 0, v68
	v_max_f32_e32 v69, 0, v69
	v_max_f32_e32 v64, 0, v64
	v_max_f32_e32 v65, 0, v65
	v_max_f32_e32 v67, 0, v67
	v_pk_mul_f32 v[68:69], v[68:69], v[68:69]
	v_pk_mul_f32 v[70:71], v[64:65], v[64:65]
	v_pk_mul_f32 v[74:75], v[66:67], v[66:67]
	v_max_f32_e32 v56, v56, v56
	v_max_f32_e32 v57, v57, v57
	v_cvt_pk_bf16_f32 v64, v68, v69
	v_cvt_pk_bf16_f32 v65, v70, v71
	v_cvt_pk_bf16_f32 v66, v72, v73
	v_cvt_pk_bf16_f32 v67, v74, v75
	v_max_f32_e32 v56, 0, v56
	v_max_f32_e32 v57, 0, v57
	global_store_dwordx4 v[80:81], v[64:67], off offset:256
	v_max_f32_e32 v60, v60, v60
	v_max_f32_e32 v61, v61, v61
	v_pk_mul_f32 v[66:67], v[56:57], v[56:57]
	v_max_f32_e32 v57, v58, v58
	v_max_f32_e32 v60, 0, v60
	v_max_f32_e32 v61, 0, v61
	v_max_f32_e32 v56, v62, v62
	v_max_f32_e32 v58, 0, v57
	v_max_f32_e32 v57, v63, v63
	v_max_f32_e32 v59, v59, v59
	v_pk_mul_f32 v[60:61], v[60:61], v[60:61]
	v_max_f32_e32 v56, 0, v56
	v_max_f32_e32 v57, 0, v57
	v_max_f32_e32 v59, 0, v59
	s_mov_b32 s13, 0x100000
	v_pk_mul_f32 v[62:63], v[56:57], v[56:57]
	v_pk_mul_f32 v[68:69], v[58:59], v[58:59]
	v_cvt_pk_bf16_f32 v56, v60, v61
	v_add_co_u32_e32 v60, vcc, s13, v138
	v_max_f32_e32 v48, v48, v48
	v_max_f32_e32 v49, v49, v49
	v_cvt_pk_bf16_f32 v57, v62, v63
	v_cvt_pk_bf16_f32 v58, v66, v67
	v_cvt_pk_bf16_f32 v59, v68, v69
	v_addc_co_u32_e32 v61, vcc, 0, v139, vcc
	v_max_f32_e32 v48, 0, v48
	v_max_f32_e32 v49, 0, v49
	global_store_dwordx4 v[60:61], v[56:59], off
	v_max_f32_e32 v52, v52, v52
	v_max_f32_e32 v53, v53, v53
	v_pk_mul_f32 v[56:57], v[48:49], v[48:49]
	v_max_f32_e32 v49, v50, v50
	v_max_f32_e32 v48, v54, v54
	v_max_f32_e32 v50, 0, v49
	v_max_f32_e32 v49, v55, v55
	v_max_f32_e32 v51, v51, v51
	v_max_f32_e32 v52, 0, v52
	v_max_f32_e32 v53, 0, v53
	v_max_f32_e32 v48, 0, v48
	v_max_f32_e32 v49, 0, v49
	v_max_f32_e32 v51, 0, v51
	s_mov_b64 s[22:23], 0x100000
	v_pk_mul_f32 v[52:53], v[52:53], v[52:53]
	v_pk_mul_f32 v[54:55], v[48:49], v[48:49]
	v_pk_mul_f32 v[58:59], v[50:51], v[50:51]
	v_max_f32_e32 v40, v40, v40
	v_max_f32_e32 v41, v41, v41
	v_lshl_add_u64 v[64:65], v[138:139], 0, s[22:23]
	v_cvt_pk_bf16_f32 v48, v52, v53
	v_cvt_pk_bf16_f32 v49, v54, v55
	v_cvt_pk_bf16_f32 v50, v56, v57
	v_cvt_pk_bf16_f32 v51, v58, v59
	v_max_f32_e32 v40, 0, v40
	v_max_f32_e32 v41, 0, v41
	global_store_dwordx4 v[64:65], v[48:51], off offset:256
	v_max_f32_e32 v44, v44, v44
	v_max_f32_e32 v45, v45, v45
	v_pk_mul_f32 v[50:51], v[40:41], v[40:41]
	v_max_f32_e32 v41, v42, v42
	v_max_f32_e32 v44, 0, v44
	v_max_f32_e32 v45, 0, v45
	v_max_f32_e32 v40, v46, v46
	v_max_f32_e32 v42, 0, v41
	v_max_f32_e32 v41, v47, v47
	v_max_f32_e32 v43, v43, v43
	v_pk_mul_f32 v[44:45], v[44:45], v[44:45]
	v_max_f32_e32 v40, 0, v40
	v_max_f32_e32 v41, 0, v41
	v_max_f32_e32 v43, 0, v43
	s_mov_b32 s13, 0x120000
	v_pk_mul_f32 v[46:47], v[40:41], v[40:41]
	v_pk_mul_f32 v[52:53], v[42:43], v[42:43]
	v_cvt_pk_bf16_f32 v40, v44, v45
	v_add_co_u32_e32 v44, vcc, s13, v138
	v_max_f32_e32 v32, v32, v32
	v_max_f32_e32 v33, v33, v33
	v_cvt_pk_bf16_f32 v41, v46, v47
	v_cvt_pk_bf16_f32 v42, v50, v51
	v_cvt_pk_bf16_f32 v43, v52, v53
	v_addc_co_u32_e32 v45, vcc, 0, v139, vcc
	v_max_f32_e32 v32, 0, v32
	v_max_f32_e32 v33, 0, v33
; __device__ __forceinline__ unsigned cvt_pk_bf16(float lo, float hi) { const f32x2 v = (f32x2){lo, hi}; return __builtin_bit_cast(unsigned, __builtin_convertvector(v, bf16v2)); }
; #define PG8_WAIT_V(n) asm volatile("s_waitcnt vmcnt(" #n ")" ::: "memory")
; #define PG8_BAR __builtin_amdgcn_s_barrier()
;     __device__ __forceinline__ void operator()(f32x4 (&acc)[2][2][4][2], const Unit& u, int wr, int wc, int fr, int fq, LAS unsigned char* xl, int wid, int lane) const {
;     ...
; #pragma unroll
;         for (int ai = 0; ai < 2; ++ai)
; #pragma unroll
;             for (int m = 0; m < 4; ++m) { bf16_t* rowp = base + (size_t)(row0 + ai * HALF + m * 16) * ldc + col0;
; #pragma unroll
;                 for (int bj = 0; bj < 2; ++bj) { f32x4 v0 = acc[ai][bj][m][0], v1 = acc[ai][bj][m][1];
;                     if (MODE == 2) {
; #pragma unroll
;                         for (int e = 0; e < 4; ++e) { const float a = fmaxf(v0[e], 0.f), b = fmaxf(v1[e], 0.f); v0[e] = a * a; v1[e] = b * b; } }
;                     u32x4 w; w.x = cvt_pk_bf16(v0[0], v0[1]); w.y = cvt_pk_bf16(v0[2], v0[3]); w.z = cvt_pk_bf16(v1[0], v1[1]); w.w = cvt_pk_bf16(v1[2], v1[3]);
;                     *(u32x4*)(rowp + bj * HALF) = w; } }
; template <class EpiT, bool ALIGN_EPI>
; __device__ __forceinline__ void gemm_phase(LAS unsigned char* lds, const Gemm g, const StaticOrder& S, const EpiT& E, const int tid) {
;     ...
;         cur = nxt; cA = nA; cB = nB; ++ui;
;         if constexpr (ALIGN_EPI) { if (wr == 1) PG8_BAR; }
;     }
;     PG8_WAIT_V(0);
;     if constexpr (!ALIGN_EPI) { if (wr == 0) PG8_BAR; }
;     PG8_BAR;
	global_store_dwordx4 v[44:45], v[40:43], off
	v_max_f32_e32 v36, v36, v36
	v_max_f32_e32 v37, v37, v37
	v_pk_mul_f32 v[40:41], v[32:33], v[32:33]
	v_max_f32_e32 v33, v34, v34
	v_max_f32_e32 v32, v38, v38
	v_max_f32_e32 v34, 0, v33
	v_max_f32_e32 v33, v39, v39
	v_max_f32_e32 v35, v35, v35
	v_max_f32_e32 v36, 0, v36
	v_max_f32_e32 v37, 0, v37
	v_max_f32_e32 v32, 0, v32
	v_max_f32_e32 v33, 0, v33
	v_max_f32_e32 v35, 0, v35
	s_mov_b64 s[22:23], 0x120000
	v_pk_mul_f32 v[36:37], v[36:37], v[36:37]
	v_pk_mul_f32 v[38:39], v[32:33], v[32:33]
	v_pk_mul_f32 v[42:43], v[34:35], v[34:35]
	v_max_f32_e32 v24, v24, v24
	v_max_f32_e32 v25, v25, v25
	v_lshl_add_u64 v[48:49], v[138:139], 0, s[22:23]
	v_cvt_pk_bf16_f32 v32, v36, v37
	v_cvt_pk_bf16_f32 v33, v38, v39
	v_cvt_pk_bf16_f32 v34, v40, v41
	v_cvt_pk_bf16_f32 v35, v42, v43
	v_max_f32_e32 v24, 0, v24
	v_max_f32_e32 v25, 0, v25
	global_store_dwordx4 v[48:49], v[32:35], off offset:256
	v_max_f32_e32 v28, v28, v28
	v_max_f32_e32 v29, v29, v29
	v_pk_mul_f32 v[34:35], v[24:25], v[24:25]
	v_max_f32_e32 v25, v26, v26
	v_max_f32_e32 v28, 0, v28
	v_max_f32_e32 v29, 0, v29
	v_max_f32_e32 v24, v30, v30
	v_max_f32_e32 v26, 0, v25
	v_max_f32_e32 v25, v31, v31
	v_max_f32_e32 v27, v27, v27
	v_pk_mul_f32 v[28:29], v[28:29], v[28:29]
	v_max_f32_e32 v24, 0, v24
	v_max_f32_e32 v25, 0, v25
	v_max_f32_e32 v27, 0, v27
	s_mov_b32 s13, 0x140000
	v_pk_mul_f32 v[30:31], v[24:25], v[24:25]
	v_pk_mul_f32 v[36:37], v[26:27], v[26:27]
	v_cvt_pk_bf16_f32 v24, v28, v29
	v_add_co_u32_e32 v28, vcc, s13, v138
	v_max_f32_e32 v16, v16, v16
	v_max_f32_e32 v17, v17, v17
	v_cvt_pk_bf16_f32 v25, v30, v31
	v_cvt_pk_bf16_f32 v26, v34, v35
	v_cvt_pk_bf16_f32 v27, v36, v37
	v_addc_co_u32_e32 v29, vcc, 0, v139, vcc
	v_max_f32_e32 v16, 0, v16
	v_max_f32_e32 v17, 0, v17
	global_store_dwordx4 v[28:29], v[24:27], off
	v_max_f32_e32 v20, v20, v20
	v_max_f32_e32 v21, v21, v21
	v_pk_mul_f32 v[24:25], v[16:17], v[16:17]
	v_max_f32_e32 v17, v18, v18
	v_max_f32_e32 v16, v22, v22
	v_max_f32_e32 v18, 0, v17
	v_max_f32_e32 v17, v23, v23
	v_max_f32_e32 v19, v19, v19
	v_max_f32_e32 v20, 0, v20
	v_max_f32_e32 v21, 0, v21
	v_max_f32_e32 v16, 0, v16
	v_max_f32_e32 v17, 0, v17
	v_max_f32_e32 v19, 0, v19
	s_mov_b64 s[22:23], 0x140000
	v_pk_mul_f32 v[20:21], v[20:21], v[20:21]
	v_pk_mul_f32 v[22:23], v[16:17], v[16:17]
	v_pk_mul_f32 v[26:27], v[18:19], v[18:19]
	v_max_f32_e32 v8, v8, v8
	v_max_f32_e32 v9, v9, v9
	v_lshl_add_u64 v[32:33], v[138:139], 0, s[22:23]
	v_cvt_pk_bf16_f32 v16, v20, v21
	v_cvt_pk_bf16_f32 v17, v22, v23
	v_cvt_pk_bf16_f32 v18, v24, v25
	v_cvt_pk_bf16_f32 v19, v26, v27
	v_max_f32_e32 v8, 0, v8
	v_max_f32_e32 v9, 0, v9
	global_store_dwordx4 v[32:33], v[16:19], off offset:256
	v_max_f32_e32 v12, v12, v12
	v_max_f32_e32 v13, v13, v13
	v_pk_mul_f32 v[18:19], v[8:9], v[8:9]
	v_max_f32_e32 v9, v10, v10
	v_max_f32_e32 v12, 0, v12
	v_max_f32_e32 v13, 0, v13
	v_max_f32_e32 v8, v14, v14
	v_max_f32_e32 v10, 0, v9
	v_max_f32_e32 v9, v15, v15
	v_max_f32_e32 v11, v11, v11
	v_pk_mul_f32 v[12:13], v[12:13], v[12:13]
	v_max_f32_e32 v8, 0, v8
	v_max_f32_e32 v9, 0, v9
	v_max_f32_e32 v11, 0, v11
	s_mov_b32 s13, 0x160000
	v_pk_mul_f32 v[14:15], v[8:9], v[8:9]
	v_pk_mul_f32 v[20:21], v[10:11], v[10:11]
	v_cvt_pk_bf16_f32 v8, v12, v13
	v_add_co_u32_e32 v12, vcc, s13, v138
	v_max_f32_e32 v0, v0, v0
	v_max_f32_e32 v1, v1, v1
	v_cvt_pk_bf16_f32 v9, v14, v15
	v_cvt_pk_bf16_f32 v10, v18, v19
	v_cvt_pk_bf16_f32 v11, v20, v21
	v_addc_co_u32_e32 v13, vcc, 0, v139, vcc
	v_max_f32_e32 v0, 0, v0
	v_max_f32_e32 v1, 0, v1
	global_store_dwordx4 v[12:13], v[8:11], off
	v_max_f32_e32 v4, v4, v4
	v_max_f32_e32 v5, v5, v5
	v_pk_mul_f32 v[8:9], v[0:1], v[0:1]
	v_max_f32_e32 v1, v2, v2
	v_max_f32_e32 v0, v6, v6
	v_max_f32_e32 v2, 0, v1
	v_max_f32_e32 v1, v7, v7
	v_max_f32_e32 v3, v3, v3
	v_max_f32_e32 v4, 0, v4
	v_max_f32_e32 v5, 0, v5
	v_max_f32_e32 v0, 0, v0
	v_max_f32_e32 v1, 0, v1
	v_max_f32_e32 v3, 0, v3
	s_mov_b64 s[22:23], 0x160000
	v_pk_mul_f32 v[4:5], v[4:5], v[4:5]
	v_pk_mul_f32 v[6:7], v[0:1], v[0:1]
	v_pk_mul_f32 v[10:11], v[2:3], v[2:3]
	v_lshl_add_u64 v[16:17], v[138:139], 0, s[22:23]
	v_cvt_pk_bf16_f32 v0, v4, v5
	v_cvt_pk_bf16_f32 v1, v6, v7
	v_cvt_pk_bf16_f32 v2, v8, v9
	v_cvt_pk_bf16_f32 v3, v10, v11
	s_and_b64 vcc, exec, s[4:5]
	s_mov_b64 s[4:5], -1
	global_store_dwordx4 v[16:17], v[0:3], off offset:256
	s_cbranch_vccnz .LBB0_177
	s_andn2_b64 vcc, exec, s[6:7]
	s_cbranch_vccnz .LBB0_176
	s_branch .LBB0_176
.LBB0_189:
	s_waitcnt vmcnt(0)
	s_and_b64 vcc, exec, s[10:11]
	s_cbranch_vccz .Lunal_189
	s_barrier
.Lunal_189:
	s_barrier
.LBB0_190:
	s_mov_b64 s[0:1], 0

; #define PG8_STAGE(bufoff, gbase, voff) do { _Pragma("unroll") for (int _i = 0; _i < 2; ++_i) \
;         __builtin_amdgcn_global_load_lds((const unsigned*)((const char*)(gbase) + (voff)[_i]), (LAS unsigned*)(lds + (bufoff) + ldsw + _i * 8192), 16, 0, 0); } while (0)
; #define PG8_LDA(dst, b, h) do { _Pragma("unroll") for (int m = 0; m < 4; ++m) _Pragma("unroll") for (int k = 0; k < 2; ++k) dst[m][k] = *(const LAS bf16x8*)(lds + PG8_SA(b, h) + aoff + m * 2048 + k * 1024); } while (0)
; #define PG8_LDB(dst, b, h) do { _Pragma("unroll") for (int n = 0; n < 2; ++n) _Pragma("unroll") for (int k = 0; k < 2; ++k) dst[n][k] = *(const LAS bf16x8*)(lds + PG8_SB(b, h) + boff + n * 2048 + k * 1024); } while (0)
; #define PG8_MMA(ai, bj, At, Bt) do { __builtin_amdgcn_s_setprio(1); _Pragma("unroll") for (int m = 0; m < 4; ++m) _Pragma("unroll") for (int n = 0; n < 2; ++n) _Pragma("unroll") for (int k = 0; k < 2; ++k) \
;         acc[ai][bj][m][n] = __builtin_amdgcn_mfma_f32_16x16x32_bf16(Bt[n][k], At[m][k], acc[ai][bj][m][n], 0, 0, 0); __builtin_amdgcn_s_setprio(0); } while (0)
; #define PG8_WAIT_V(n) asm volatile("s_waitcnt vmcnt(" #n ")" ::: "memory")
; #define PG8_WAIT_L(n) asm volatile("s_waitcnt lgkmcnt(" #n ")" ::: "memory")
; #define PG8_BAR __builtin_amdgcn_s_barrier()
; #define PG8_SCHED __builtin_amdgcn_sched_barrier(0)
; template <class EpiT, bool ALIGN_EPI>
; __device__ __forceinline__ void gemm_phase(LAS unsigned char* lds, const Gemm g, const StaticOrder& S, const EpiT& E, const int tid) {
;     ...
;         for (int t = 0; t < nt; t += 2) {
;             const bool last = (t == nt - 2);
;             const char* a1 = cA + (size_t)(t + 1) * kstep;
;             const char* a2 = last ? nA : cA + (size_t)(t + 2) * kstep; const char* b2 = last ? nB : cB + (size_t)(t + 2) * kstep;
;             const char* a3 = a2 + kstep; const char* b3 = b2 + kstep;
;             PG8_LDB(B0, 0, 0); PG8_LDB(B1, 0, 1); PG8_SCHED; PG8_LDA(At, 0, 0); PG8_STAGE(PG8_SA(1, 1), a1 + hstep, voffA);
;             PG8_WAIT_V(8); PG8_WAIT_L(0); PG8_BAR; PG8_MMA(0, 0, At, B0); PG8_MMA(0, 1, At, B1); PG8_BAR; PG8_SCHED;
;             PG8_LDA(At, 0, 1); PG8_STAGE(PG8_SB(0, 0), b2, voffB); PG8_STAGE(PG8_SB(0, 1), b2 + hstep, voffB); PG8_STAGE(PG8_SA(0, 0), a2, voffA);
;             PG8_WAIT_V(8); PG8_WAIT_L(0); PG8_BAR; PG8_MMA(1, 0, At, B0); PG8_MMA(1, 1, At, B1); PG8_BAR; PG8_SCHED;
.LBB0_352:
	s_add_u32 s18, s16, 0xfffc0080
	s_addc_u32 s19, s17, -1
	s_add_i32 s61, 0, 0x10000
	s_cmp_eq_u32 s53, 12
	s_cselect_b32 s21, s1, s19
	s_cselect_b32 s20, s0, s18
	v_add_u32_e32 v154, s61, v139
	s_cselect_b32 s19, s15, s13
	s_cselect_b32 s18, s14, s11
	s_add_i32 s64, 0, 0x14000
	ds_read_b128 v[142:145], v154
	ds_read_b128 v[146:149], v154 offset:1024
	ds_read_b128 v[150:153], v154 offset:2048
	ds_read_b128 v[170:173], v154 offset:3072
	v_add_u32_e32 v154, s64, v139
	ds_read_b128 v[174:177], v154
	ds_read_b128 v[178:181], v154 offset:1024
	ds_read_b128 v[182:185], v154 offset:2048
	ds_read_b128 v[186:189], v154 offset:3072
	v_lshl_add_u64 v[154:155], s[16:17], 0, v[134:135]
	s_add_i32 m0, s25, 0xc000
	ds_read_b128 v[190:193], v141
	ds_read_b128 v[194:197], v141 offset:1024
	ds_read_b128 v[198:201], v141 offset:2048
	ds_read_b128 v[202:205], v141 offset:3072
	ds_read_b128 v[206:209], v141 offset:4096
	ds_read_b128 v[210:213], v141 offset:5120
	ds_read_b128 v[214:217], v141 offset:6144
	ds_read_b128 v[224:227], v141 offset:7168
	global_load_lds_dwordx4 v[154:155], off
	v_lshl_add_u64 v[154:155], s[16:17], 0, v[136:137]
	s_add_i32 m0, s25, 0xe000
	s_nop 0
	global_load_lds_dwordx4 v[154:155], off
	s_waitcnt vmcnt(8)
	s_waitcnt lgkmcnt(0)
	s_barrier
	s_setprio 1
	s_waitcnt lgkmcnt(0)
	v_mfma_f32_16x16x32_bf16 v[124:127], v[142:145], v[190:193], v[124:127]
	v_mfma_f32_16x16x32_bf16 v[120:123], v[150:153], v[190:193], v[120:123]
	v_mfma_f32_16x16x32_bf16 v[116:119], v[142:145], v[198:201], v[116:119]
	v_mfma_f32_16x16x32_bf16 v[112:115], v[150:153], v[198:201], v[112:115]
	v_mfma_f32_16x16x32_bf16 v[100:103], v[142:145], v[206:209], v[100:103]
	v_mfma_f32_16x16x32_bf16 v[96:99], v[150:153], v[206:209], v[96:99]
	v_mfma_f32_16x16x32_bf16 v[84:87], v[142:145], v[214:217], v[84:87]
	v_mfma_f32_16x16x32_bf16 v[80:83], v[150:153], v[214:217], v[80:83]
	v_mfma_f32_16x16x32_bf16 v[124:127], v[146:149], v[194:197], v[124:127]
	v_mfma_f32_16x16x32_bf16 v[120:123], v[170:173], v[194:197], v[120:123]
	v_mfma_f32_16x16x32_bf16 v[116:119], v[146:149], v[202:205], v[116:119]
	v_mfma_f32_16x16x32_bf16 v[112:115], v[170:173], v[202:205], v[112:115]
	v_mfma_f32_16x16x32_bf16 v[100:103], v[146:149], v[210:213], v[100:103]
	v_mfma_f32_16x16x32_bf16 v[96:99], v[170:173], v[210:213], v[96:99]
	v_mfma_f32_16x16x32_bf16 v[84:87], v[146:149], v[224:227], v[84:87]
	v_mfma_f32_16x16x32_bf16 v[80:83], v[170:173], v[224:227], v[80:83]
	s_setprio 0
	s_setprio 1
	v_mfma_f32_16x16x32_bf16 v[108:111], v[174:177], v[190:193], v[108:111]
	v_mfma_f32_16x16x32_bf16 v[104:107], v[182:185], v[190:193], v[104:107]
	v_mfma_f32_16x16x32_bf16 v[92:95], v[174:177], v[198:201], v[92:95]
	v_mfma_f32_16x16x32_bf16 v[88:91], v[182:185], v[198:201], v[88:91]
	v_mfma_f32_16x16x32_bf16 v[76:79], v[174:177], v[206:209], v[76:79]
	v_mfma_f32_16x16x32_bf16 v[72:75], v[182:185], v[206:209], v[72:75]
	v_mfma_f32_16x16x32_bf16 v[68:71], v[174:177], v[214:217], v[68:71]
	v_mfma_f32_16x16x32_bf16 v[64:67], v[182:185], v[214:217], v[64:67]
	v_mfma_f32_16x16x32_bf16 v[108:111], v[178:181], v[194:197], v[108:111]
	v_mfma_f32_16x16x32_bf16 v[104:107], v[186:189], v[194:197], v[104:107]
	v_mfma_f32_16x16x32_bf16 v[92:95], v[178:181], v[202:205], v[92:95]
	v_mfma_f32_16x16x32_bf16 v[88:91], v[186:189], v[202:205], v[88:91]
	v_mfma_f32_16x16x32_bf16 v[76:79], v[178:181], v[210:213], v[76:79]
	v_mfma_f32_16x16x32_bf16 v[72:75], v[186:189], v[210:213], v[72:75]
	v_mfma_f32_16x16x32_bf16 v[68:71], v[178:181], v[224:227], v[68:71]
	v_mfma_f32_16x16x32_bf16 v[64:67], v[186:189], v[224:227], v[64:67]
	s_setprio 0
	s_barrier
	s_add_i32 s61, s61, s24
	v_lshl_add_u64 v[154:155], s[18:19], 0, v[156:157]
	s_mov_b32 m0, s61
	ds_read_b128 v[190:193], v141 offset:16384
	ds_read_b128 v[194:197], v141 offset:17408
	ds_read_b128 v[198:201], v141 offset:18432
	ds_read_b128 v[202:205], v141 offset:19456
	ds_read_b128 v[206:209], v141 offset:20480
	ds_read_b128 v[210:213], v141 offset:21504
	ds_read_b128 v[214:217], v141 offset:22528
	ds_read_b128 v[224:227], v141 offset:23552
	global_load_lds_dwordx4 v[154:155], off
	s_add_i32 m0, s61, 0x2000
	s_add_u32 s62, s18, 0x40000
	v_lshl_add_u64 v[228:229], s[18:19], 0, v[128:129]
	s_addc_u32 s63, s19, 0
	s_add_i32 s61, s64, s24
	global_load_lds_dwordx4 v[228:229], off
	v_lshl_add_u64 v[230:231], s[62:63], 0, v[156:157]
	s_mov_b32 m0, s61
	v_lshl_add_u64 v[232:233], s[20:21], 0, v[130:131]
	global_load_lds_dwordx4 v[230:231], off
	v_lshl_add_u64 v[230:231], s[62:63], 0, v[128:129]
	s_add_i32 m0, s61, 0x2000
	s_nop 0
	global_load_lds_dwordx4 v[230:231], off
	v_lshl_add_u64 v[230:231], s[20:21], 0, v[132:133]
	s_mov_b32 m0, s25
	s_nop 0
	global_load_lds_dwordx4 v[230:231], off
	s_mov_b32 m0, s26
	s_nop 0
	global_load_lds_dwordx4 v[232:233], off
	s_waitcnt vmcnt(8)
	s_waitcnt lgkmcnt(0)
	s_barrier
; #define PG8_STAGE(bufoff, gbase, voff) do { _Pragma("unroll") for (int _i = 0; _i < 2; ++_i) \
;         __builtin_amdgcn_global_load_lds((const unsigned*)((const char*)(gbase) + (voff)[_i]), (LAS unsigned*)(lds + (bufoff) + ldsw + _i * 8192), 16, 0, 0); } while (0)
; #define PG8_LDA(dst, b, h) do { _Pragma("unroll") for (int m = 0; m < 4; ++m) _Pragma("unroll") for (int k = 0; k < 2; ++k) dst[m][k] = *(const LAS bf16x8*)(lds + PG8_SA(b, h) + aoff + m * 2048 + k * 1024); } while (0)
; #define PG8_LDB(dst, b, h) do { _Pragma("unroll") for (int n = 0; n < 2; ++n) _Pragma("unroll") for (int k = 0; k < 2; ++k) dst[n][k] = *(const LAS bf16x8*)(lds + PG8_SB(b, h) + boff + n * 2048 + k * 1024); } while (0)
; #define PG8_MMA(ai, bj, At, Bt) do { __builtin_amdgcn_s_setprio(1); _Pragma("unroll") for (int m = 0; m < 4; ++m) _Pragma("unroll") for (int n = 0; n < 2; ++n) _Pragma("unroll") for (int k = 0; k < 2; ++k) \
;         acc[ai][bj][m][n] = __builtin_amdgcn_mfma_f32_16x16x32_bf16(Bt[n][k], At[m][k], acc[ai][bj][m][n], 0, 0, 0); __builtin_amdgcn_s_setprio(0); } while (0)
; #define PG8_WAIT_V(n) asm volatile("s_waitcnt vmcnt(" #n ")" ::: "memory")
; #define PG8_WAIT_L(n) asm volatile("s_waitcnt lgkmcnt(" #n ")" ::: "memory")
; #define PG8_BAR __builtin_amdgcn_s_barrier()
; #define PG8_SCHED __builtin_amdgcn_sched_barrier(0)
; template <class EpiT, bool ALIGN_EPI>
; __device__ __forceinline__ void gemm_phase(LAS unsigned char* lds, const Gemm g, const StaticOrder& S, const EpiT& E, const int tid) {
;     ...
;             PG8_WAIT_V(8); PG8_WAIT_L(0); PG8_BAR; PG8_MMA(1, 0, At, B0); PG8_MMA(1, 1, At, B1); PG8_BAR; PG8_SCHED;
;             PG8_LDB(B0, 1, 0); PG8_LDB(B1, 1, 1); PG8_SCHED; PG8_LDA(At, 1, 0); PG8_STAGE(PG8_SA(0, 1), a2 + hstep, voffA);
;             PG8_WAIT_V(8); PG8_WAIT_L(0); PG8_BAR; PG8_MMA(0, 0, At, B0); PG8_MMA(0, 1, At, B1); PG8_BAR; PG8_SCHED;
;             PG8_LDA(At, 1, 1); PG8_STAGE(PG8_SB(1, 0), b3, voffB); PG8_STAGE(PG8_SB(1, 1), b3 + hstep, voffB); PG8_STAGE(PG8_SA(1, 0), a3, voffA);
;             PG8_WAIT_V(8); PG8_WAIT_L(0); PG8_BAR; PG8_MMA(1, 0, At, B0); PG8_MMA(1, 1, At, B1); PG8_BAR; PG8_SCHED;
	s_setprio 1
	s_waitcnt lgkmcnt(0)
	v_mfma_f32_16x16x32_bf16 v[60:63], v[142:145], v[190:193], v[60:63]
	v_mfma_f32_16x16x32_bf16 v[56:59], v[150:153], v[190:193], v[56:59]
	v_mfma_f32_16x16x32_bf16 v[52:55], v[142:145], v[198:201], v[52:55]
	v_mfma_f32_16x16x32_bf16 v[48:51], v[150:153], v[198:201], v[48:51]
	v_mfma_f32_16x16x32_bf16 v[36:39], v[142:145], v[206:209], v[36:39]
	v_mfma_f32_16x16x32_bf16 v[32:35], v[150:153], v[206:209], v[32:35]
	v_mfma_f32_16x16x32_bf16 v[20:23], v[142:145], v[214:217], v[20:23]
	v_mfma_f32_16x16x32_bf16 v[16:19], v[150:153], v[214:217], v[16:19]
	v_mfma_f32_16x16x32_bf16 v[60:63], v[146:149], v[194:197], v[60:63]
	v_mfma_f32_16x16x32_bf16 v[56:59], v[170:173], v[194:197], v[56:59]
	v_mfma_f32_16x16x32_bf16 v[52:55], v[146:149], v[202:205], v[52:55]
	v_mfma_f32_16x16x32_bf16 v[48:51], v[170:173], v[202:205], v[48:51]
	v_mfma_f32_16x16x32_bf16 v[36:39], v[146:149], v[210:213], v[36:39]
	v_mfma_f32_16x16x32_bf16 v[32:35], v[170:173], v[210:213], v[32:35]
	v_mfma_f32_16x16x32_bf16 v[20:23], v[146:149], v[224:227], v[20:23]
	v_mfma_f32_16x16x32_bf16 v[16:19], v[170:173], v[224:227], v[16:19]
	s_setprio 0
	s_setprio 1
	v_mfma_f32_16x16x32_bf16 v[44:47], v[174:177], v[190:193], v[44:47]
	v_mfma_f32_16x16x32_bf16 v[40:43], v[182:185], v[190:193], v[40:43]
	v_mfma_f32_16x16x32_bf16 v[28:31], v[174:177], v[198:201], v[28:31]
	v_mfma_f32_16x16x32_bf16 v[24:27], v[182:185], v[198:201], v[24:27]
	v_mfma_f32_16x16x32_bf16 v[12:15], v[174:177], v[206:209], v[12:15]
	v_mfma_f32_16x16x32_bf16 v[8:11], v[182:185], v[206:209], v[8:11]
	v_mfma_f32_16x16x32_bf16 v[4:7], v[174:177], v[214:217], v[4:7]
	v_mfma_f32_16x16x32_bf16 v[0:3], v[182:185], v[214:217], v[0:3]
	v_mfma_f32_16x16x32_bf16 v[44:47], v[178:181], v[194:197], v[44:47]
	v_mfma_f32_16x16x32_bf16 v[40:43], v[186:189], v[194:197], v[40:43]
	v_mfma_f32_16x16x32_bf16 v[28:31], v[178:181], v[202:205], v[28:31]
	v_mfma_f32_16x16x32_bf16 v[24:27], v[186:189], v[202:205], v[24:27]
	v_mfma_f32_16x16x32_bf16 v[12:15], v[178:181], v[210:213], v[12:15]
	v_mfma_f32_16x16x32_bf16 v[8:11], v[186:189], v[210:213], v[8:11]
	v_mfma_f32_16x16x32_bf16 v[4:7], v[178:181], v[224:227], v[4:7]
	v_mfma_f32_16x16x32_bf16 v[0:3], v[186:189], v[224:227], v[0:3]
	s_setprio 0
	s_barrier
	s_add_i32 s61, 0, 0x18000
	v_add_u32_e32 v160, s61, v139
	s_add_i32 s62, 0, 0x1c000
	ds_read_b128 v[142:145], v160
	ds_read_b128 v[146:149], v160 offset:1024
	ds_read_b128 v[150:153], v160 offset:2048
	ds_read_b128 v[170:173], v160 offset:3072
	v_add_u32_e32 v160, s62, v139
	ds_read_b128 v[174:177], v160
	ds_read_b128 v[178:181], v160 offset:1024
	ds_read_b128 v[182:185], v160 offset:2048
	ds_read_b128 v[186:189], v160 offset:3072
	s_add_u32 s20, s20, 0x40000
	s_addc_u32 s21, s21, 0
	s_mov_b32 m0, s27
	v_lshl_add_u64 v[234:235], s[20:21], 0, v[132:133]
	ds_read_b128 v[190:193], v141 offset:32768
	ds_read_b128 v[194:197], v141 offset:33792
	ds_read_b128 v[198:201], v141 offset:34816
	ds_read_b128 v[202:205], v141 offset:35840
	ds_read_b128 v[206:209], v141 offset:36864
	ds_read_b128 v[210:213], v141 offset:37888
	ds_read_b128 v[214:217], v141 offset:38912
	ds_read_b128 v[224:227], v141 offset:39936
	global_load_lds_dwordx4 v[234:235], off
	v_lshl_add_u64 v[234:235], s[20:21], 0, v[130:131]
	s_mov_b32 m0, s28
	s_nop 0
	global_load_lds_dwordx4 v[234:235], off
	s_waitcnt vmcnt(8)
	s_waitcnt lgkmcnt(0)
	s_barrier
	s_setprio 1
	s_waitcnt lgkmcnt(0)
	v_mfma_f32_16x16x32_bf16 v[124:127], v[142:145], v[190:193], v[124:127]
	v_mfma_f32_16x16x32_bf16 v[120:123], v[150:153], v[190:193], v[120:123]
	v_mfma_f32_16x16x32_bf16 v[116:119], v[142:145], v[198:201], v[116:119]
	v_mfma_f32_16x16x32_bf16 v[112:115], v[150:153], v[198:201], v[112:115]
	v_mfma_f32_16x16x32_bf16 v[100:103], v[142:145], v[206:209], v[100:103]
	v_mfma_f32_16x16x32_bf16 v[96:99], v[150:153], v[206:209], v[96:99]
	v_mfma_f32_16x16x32_bf16 v[84:87], v[142:145], v[214:217], v[84:87]
	v_mfma_f32_16x16x32_bf16 v[80:83], v[150:153], v[214:217], v[80:83]
	v_mfma_f32_16x16x32_bf16 v[124:127], v[146:149], v[194:197], v[124:127]
	v_mfma_f32_16x16x32_bf16 v[120:123], v[170:173], v[194:197], v[120:123]
	v_mfma_f32_16x16x32_bf16 v[116:119], v[146:149], v[202:205], v[116:119]
	v_mfma_f32_16x16x32_bf16 v[112:115], v[170:173], v[202:205], v[112:115]
	v_mfma_f32_16x16x32_bf16 v[100:103], v[146:149], v[210:213], v[100:103]
	v_mfma_f32_16x16x32_bf16 v[96:99], v[170:173], v[210:213], v[96:99]
	v_mfma_f32_16x16x32_bf16 v[84:87], v[146:149], v[224:227], v[84:87]
	v_mfma_f32_16x16x32_bf16 v[80:83], v[170:173], v[224:227], v[80:83]
	s_setprio 0
	s_setprio 1
	v_mfma_f32_16x16x32_bf16 v[108:111], v[174:177], v[190:193], v[108:111]
	v_mfma_f32_16x16x32_bf16 v[104:107], v[182:185], v[190:193], v[104:107]
	v_mfma_f32_16x16x32_bf16 v[92:95], v[174:177], v[198:201], v[92:95]
	v_mfma_f32_16x16x32_bf16 v[88:91], v[182:185], v[198:201], v[88:91]
	v_mfma_f32_16x16x32_bf16 v[76:79], v[174:177], v[206:209], v[76:79]
	v_mfma_f32_16x16x32_bf16 v[72:75], v[182:185], v[206:209], v[72:75]
	v_mfma_f32_16x16x32_bf16 v[68:71], v[174:177], v[214:217], v[68:71]
	v_mfma_f32_16x16x32_bf16 v[64:67], v[182:185], v[214:217], v[64:67]
	v_mfma_f32_16x16x32_bf16 v[108:111], v[178:181], v[194:197], v[108:111]
	v_mfma_f32_16x16x32_bf16 v[104:107], v[186:189], v[194:197], v[104:107]
	v_mfma_f32_16x16x32_bf16 v[92:95], v[178:181], v[202:205], v[92:95]
	v_mfma_f32_16x16x32_bf16 v[88:91], v[186:189], v[202:205], v[88:91]
	v_mfma_f32_16x16x32_bf16 v[76:79], v[178:181], v[210:213], v[76:79]
	v_mfma_f32_16x16x32_bf16 v[72:75], v[186:189], v[210:213], v[72:75]
	v_mfma_f32_16x16x32_bf16 v[68:71], v[178:181], v[224:227], v[68:71]
	v_mfma_f32_16x16x32_bf16 v[64:67], v[186:189], v[224:227], v[64:67]
	s_setprio 0
	s_barrier
; #define PG8_STAGE(bufoff, gbase, voff) do { _Pragma("unroll") for (int _i = 0; _i < 2; ++_i) \
;         __builtin_amdgcn_global_load_lds((const unsigned*)((const char*)(gbase) + (voff)[_i]), (LAS unsigned*)(lds + (bufoff) + ldsw + _i * 8192), 16, 0, 0); } while (0)
; #define PG8_LDA(dst, b, h) do { _Pragma("unroll") for (int m = 0; m < 4; ++m) _Pragma("unroll") for (int k = 0; k < 2; ++k) dst[m][k] = *(const LAS bf16x8*)(lds + PG8_SA(b, h) + aoff + m * 2048 + k * 1024); } while (0)
; #define PG8_LDB(dst, b, h) do { _Pragma("unroll") for (int n = 0; n < 2; ++n) _Pragma("unroll") for (int k = 0; k < 2; ++k) dst[n][k] = *(const LAS bf16x8*)(lds + PG8_SB(b, h) + boff + n * 2048 + k * 1024); } while (0)
; #define PG8_MMA(ai, bj, At, Bt) do { __builtin_amdgcn_s_setprio(1); _Pragma("unroll") for (int m = 0; m < 4; ++m) _Pragma("unroll") for (int n = 0; n < 2; ++n) _Pragma("unroll") for (int k = 0; k < 2; ++k) \
;         acc[ai][bj][m][n] = __builtin_amdgcn_mfma_f32_16x16x32_bf16(Bt[n][k], At[m][k], acc[ai][bj][m][n], 0, 0, 0); __builtin_amdgcn_s_setprio(0); } while (0)
; #define PG8_WAIT_V(n) asm volatile("s_waitcnt vmcnt(" #n ")" ::: "memory")
; #define PG8_WAIT_L(n) asm volatile("s_waitcnt lgkmcnt(" #n ")" ::: "memory")
; #define PG8_BAR __builtin_amdgcn_s_barrier()
; #define PG8_SCHED __builtin_amdgcn_sched_barrier(0)
;     __device__ __forceinline__ void operator()(f32x4 (&acc)[2][2][4][2], const Unit& u, int wr, int wc, int fr, int fq, LAS unsigned char* xl, int wid, int lane) const {
;     ...
;         if (MODE == 0 && u.pn >= 6) { prow = u.pn - 6; pcol = u.pm; base = O2; ldc = VTP; }
; template <class EpiT, bool ALIGN_EPI>
; __device__ __forceinline__ void gemm_phase(LAS unsigned char* lds, const Gemm g, const StaticOrder& S, const EpiT& E, const int tid) {
;     ...
;             PG8_LDB(B0, 1, 0); PG8_LDB(B1, 1, 1); PG8_SCHED; PG8_LDA(At, 1, 0); PG8_STAGE(PG8_SA(0, 1), a2 + hstep, voffA);
;             PG8_WAIT_V(8); PG8_WAIT_L(0); PG8_BAR; PG8_MMA(0, 0, At, B0); PG8_MMA(0, 1, At, B1); PG8_BAR; PG8_SCHED;
;             PG8_LDA(At, 1, 1); PG8_STAGE(PG8_SB(1, 0), b3, voffB); PG8_STAGE(PG8_SB(1, 1), b3 + hstep, voffB); PG8_STAGE(PG8_SA(1, 0), a3, voffA);
;             PG8_WAIT_V(8); PG8_WAIT_L(0); PG8_BAR; PG8_MMA(1, 0, At, B0); PG8_MMA(1, 1, At, B1); PG8_BAR; PG8_SCHED;
;         }
;         if constexpr (ALIGN_EPI) { if (wr == 0) PG8_BAR; }
	s_add_i32 s20, s61, s24
	v_lshl_add_u64 v[154:155], v[154:155], 0, s[88:89]
	s_mov_b32 m0, s20
	ds_read_b128 v[190:193], v141 offset:49152
	ds_read_b128 v[194:197], v141 offset:50176
	ds_read_b128 v[198:201], v141 offset:51200
	ds_read_b128 v[202:205], v141 offset:52224
	ds_read_b128 v[206:209], v141 offset:53248
	ds_read_b128 v[210:213], v141 offset:54272
	ds_read_b128 v[214:217], v141 offset:55296
	ds_read_b128 v[224:227], v141 offset:56320
	global_load_lds_dwordx4 v[154:155], off
	s_add_i32 m0, s20, 0x2000
	s_add_u32 s18, s18, 0x40080
	v_lshl_add_u64 v[154:155], v[228:229], 0, s[88:89]
	s_addc_u32 s19, s19, 0
	s_add_i32 s20, s62, s24
	global_load_lds_dwordx4 v[154:155], off
	v_lshl_add_u64 v[154:155], s[18:19], 0, v[156:157]
	s_mov_b32 m0, s20
	s_nop 0
	global_load_lds_dwordx4 v[154:155], off
	v_lshl_add_u64 v[154:155], s[18:19], 0, v[128:129]
	s_add_i32 m0, s20, 0x2000
	s_nop 0
	global_load_lds_dwordx4 v[154:155], off
	v_lshl_add_u64 v[154:155], v[230:231], 0, s[88:89]
	s_mov_b32 m0, s29
	s_nop 0
	global_load_lds_dwordx4 v[154:155], off
	v_lshl_add_u64 v[154:155], v[232:233], 0, s[88:89]
	s_mov_b32 m0, s30
	s_nop 0
	global_load_lds_dwordx4 v[154:155], off
	s_waitcnt vmcnt(8)
	s_waitcnt lgkmcnt(0)
	s_barrier
	s_setprio 1
	s_waitcnt lgkmcnt(0)
	v_mfma_f32_16x16x32_bf16 v[60:63], v[142:145], v[190:193], v[60:63]
	v_mfma_f32_16x16x32_bf16 v[56:59], v[150:153], v[190:193], v[56:59]
	v_mfma_f32_16x16x32_bf16 v[52:55], v[142:145], v[198:201], v[52:55]
	v_mfma_f32_16x16x32_bf16 v[48:51], v[150:153], v[198:201], v[48:51]
	v_mfma_f32_16x16x32_bf16 v[36:39], v[142:145], v[206:209], v[36:39]
	v_mfma_f32_16x16x32_bf16 v[32:35], v[150:153], v[206:209], v[32:35]
	v_mfma_f32_16x16x32_bf16 v[20:23], v[142:145], v[214:217], v[20:23]
	v_mfma_f32_16x16x32_bf16 v[16:19], v[150:153], v[214:217], v[16:19]
	v_mfma_f32_16x16x32_bf16 v[60:63], v[146:149], v[194:197], v[60:63]
	v_mfma_f32_16x16x32_bf16 v[56:59], v[170:173], v[194:197], v[56:59]
	v_mfma_f32_16x16x32_bf16 v[52:55], v[146:149], v[202:205], v[52:55]
	v_mfma_f32_16x16x32_bf16 v[48:51], v[170:173], v[202:205], v[48:51]
	v_mfma_f32_16x16x32_bf16 v[36:39], v[146:149], v[210:213], v[36:39]
	v_mfma_f32_16x16x32_bf16 v[32:35], v[170:173], v[210:213], v[32:35]
	v_mfma_f32_16x16x32_bf16 v[20:23], v[146:149], v[224:227], v[20:23]
	v_mfma_f32_16x16x32_bf16 v[16:19], v[170:173], v[224:227], v[16:19]
	s_setprio 0
	s_setprio 1
	v_mfma_f32_16x16x32_bf16 v[44:47], v[174:177], v[190:193], v[44:47]
	v_mfma_f32_16x16x32_bf16 v[40:43], v[182:185], v[190:193], v[40:43]
	v_mfma_f32_16x16x32_bf16 v[28:31], v[174:177], v[198:201], v[28:31]
	v_mfma_f32_16x16x32_bf16 v[24:27], v[182:185], v[198:201], v[24:27]
	v_mfma_f32_16x16x32_bf16 v[12:15], v[174:177], v[206:209], v[12:15]
	v_mfma_f32_16x16x32_bf16 v[8:11], v[182:185], v[206:209], v[8:11]
	v_mfma_f32_16x16x32_bf16 v[4:7], v[174:177], v[214:217], v[4:7]
	v_mfma_f32_16x16x32_bf16 v[0:3], v[182:185], v[214:217], v[0:3]
	v_mfma_f32_16x16x32_bf16 v[44:47], v[178:181], v[194:197], v[44:47]
	v_mfma_f32_16x16x32_bf16 v[40:43], v[186:189], v[194:197], v[40:43]
	v_mfma_f32_16x16x32_bf16 v[28:31], v[178:181], v[202:205], v[28:31]
	v_mfma_f32_16x16x32_bf16 v[24:27], v[186:189], v[202:205], v[24:27]
	v_mfma_f32_16x16x32_bf16 v[12:15], v[178:181], v[210:213], v[12:15]
	v_mfma_f32_16x16x32_bf16 v[8:11], v[186:189], v[210:213], v[8:11]
	v_mfma_f32_16x16x32_bf16 v[4:7], v[178:181], v[224:227], v[4:7]
	v_mfma_f32_16x16x32_bf16 v[0:3], v[186:189], v[224:227], v[0:3]
	s_setprio 0
	s_barrier
	s_add_i32 s53, s53, 2
	s_add_u32 s16, s16, 0x100
	s_addc_u32 s17, s17, 0
	s_add_u32 s11, s11, 0x100
	s_addc_u32 s13, s13, 0
	s_cmp_gt_u32 s53, 13
	s_cbranch_scc0 .LBB0_352
	s_and_b64 vcc, exec, s[8:9]
	s_cbranch_vccz .LBB0_355
.LBB0_355:
	s_cmp_lt_i32 s35, 6
	s_cbranch_scc1 .LBB0_357
	s_add_i32 s11, s35, -6
	s_mov_b64 s[18:19], 0x10e00000
	s_mov_b64 s[16:17], 0x8880
	s_mov_b32 s35, s34
	s_mov_b32 s34, s11
	s_branch .LBB0_358

; __device__ __forceinline__ unsigned cvt_pk_bf16(float lo, float hi) { const f32x2 v = (f32x2){lo, hi}; return __builtin_bit_cast(unsigned, __builtin_convertvector(v, bf16v2)); }
;     __device__ __forceinline__ void operator()(f32x4 (&acc)[2][2][4][2], const Unit& u, int wr, int wc, int fr, int fq, LAS unsigned char* xl, int wid, int lane) const {
;         int prow = u.pm, pcol = u.pn; bf16_t* base = O; size_t ldc = (MODE == 0) ? PBW : (MODE == 1 ? DM : FF);
;         if (MODE == 0 && u.pn >= 6) { prow = u.pn - 6; pcol = u.pm; base = O2; ldc = VTP; }
;         const int row0 = prow * BM + wr * 64 + fr, col0 = pcol * BM + wc * 32 + 8 * fq;
;         if (MODE == 1 && u.ks >= 0) {
;             float* pb = part + ((size_t)u.ks * MC + (size_t)(row0 - ML)) * DM + col0;
; #pragma unroll
;             for (int ai = 0; ai < 2; ++ai)
; #pragma unroll
;                 for (int m = 0; m < 4; ++m) { float* rowp = pb + (size_t)(ai * HALF + m * 16) * DM;
; #pragma unroll
;                     for (int bj = 0; bj < 2; ++bj) { *(f32x4*)(rowp + bj * HALF) = acc[ai][bj][m][0]; *(f32x4*)(rowp + bj * HALF + 4) = acc[ai][bj][m][1]; } }
;             return;
;         }
;         if (MODE == 1) { fused_epi(acc, u, wr, wc, fr, fq, xl, wid, lane, f); return; }
; #pragma unroll
;         for (int ai = 0; ai < 2; ++ai)
; #pragma unroll
;             for (int m = 0; m < 4; ++m) { bf16_t* rowp = base + (size_t)(row0 + ai * HALF + m * 16) * ldc + col0;
; #pragma unroll
;                 for (int bj = 0; bj < 2; ++bj) { f32x4 v0 = acc[ai][bj][m][0], v1 = acc[ai][bj][m][1];
;                     if (MODE == 2) {
; #pragma unroll
;                         for (int e = 0; e < 4; ++e) { const float a = fmaxf(v0[e], 0.f), b = fmaxf(v1[e], 0.f); v0[e] = a * a; v1[e] = b * b; } }
;                     u32x4 w; w.x = cvt_pk_bf16(v0[0], v0[1]); w.y = cvt_pk_bf16(v0[2], v0[3]); w.z = cvt_pk_bf16(v1[0], v1[1]); w.w = cvt_pk_bf16(v1[2], v1[3]);
;                     *(u32x4*)(rowp + bj * HALF) = w; } }
; template <class EpiT, bool ALIGN_EPI>
; __device__ __forceinline__ void gemm_phase(LAS unsigned char* lds, const Gemm g, const StaticOrder& S, const EpiT& E, const int tid) {
;     ...
;         cur = nxt; cA = nA; cB = nB; ++ui;
;         if constexpr (ALIGN_EPI) { if (wr == 1) PG8_BAR; }
;     }
;     PG8_WAIT_V(0);
;     if constexpr (!ALIGN_EPI) { if (wr == 0) PG8_BAR; }
;     PG8_BAR;
.LBB0_358:
	s_add_u32 s18, s73, s18
	v_lshl_or_b32 v142, s35, 8, v140
	s_addc_u32 s19, s57, s19
	v_lshl_add_u32 v146, s34, 8, v138
	v_ashrrev_i32_e32 v143, 31, v142
	v_lshl_add_u64 v[142:143], v[142:143], 1, s[18:19]
	v_mad_i64_i32 v[144:145], s[18:19], s16, v146, 0
	v_cvt_pk_bf16_f32 v108, v108, v109
	v_cvt_pk_bf16_f32 v109, v110, v111
	v_cvt_pk_bf16_f32 v110, v104, v105
	v_or_b32_e32 v104, 16, v146
	v_lshl_add_u64 v[144:145], v[144:145], 1, v[142:143]
	v_cvt_pk_bf16_f32 v111, v106, v107
	v_mad_i64_i32 v[104:105], s[18:19], s16, v104, 0
	v_cvt_pk_bf16_f32 v92, v92, v93
	v_cvt_pk_bf16_f32 v93, v94, v95
	v_cvt_pk_bf16_f32 v94, v88, v89
	v_or_b32_e32 v88, 32, v146
	v_cvt_pk_bf16_f32 v124, v124, v125
	v_cvt_pk_bf16_f32 v125, v126, v127
	v_cvt_pk_bf16_f32 v126, v120, v121
	v_cvt_pk_bf16_f32 v127, v122, v123
	global_store_dwordx4 v[144:145], v[108:111], off offset:256
	v_cvt_pk_bf16_f32 v95, v90, v91
	v_mad_i64_i32 v[88:89], s[18:19], s16, v88, 0
	v_lshl_add_u64 v[108:109], v[104:105], 1, v[142:143]
	v_cvt_pk_bf16_f32 v76, v76, v77
	v_cvt_pk_bf16_f32 v77, v78, v79
	v_cvt_pk_bf16_f32 v78, v72, v73
	v_or_b32_e32 v72, 48, v146
	v_cvt_pk_bf16_f32 v68, v68, v69
	v_cvt_pk_bf16_f32 v69, v70, v71
	v_cvt_pk_bf16_f32 v70, v64, v65
	v_add_u32_e32 v64, 0x80, v146
	global_store_dwordx4 v[144:145], v[124:127], off
	v_cvt_pk_bf16_f32 v104, v116, v117
	v_cvt_pk_bf16_f32 v105, v118, v119
	v_cvt_pk_bf16_f32 v106, v112, v113
	v_cvt_pk_bf16_f32 v107, v114, v115
	global_store_dwordx4 v[108:109], v[92:95], off offset:256
	v_cvt_pk_bf16_f32 v79, v74, v75
	v_mad_i64_i32 v[72:73], s[18:19], s16, v72, 0
	v_lshl_add_u64 v[92:93], v[88:89], 1, v[142:143]
	v_mad_i64_i32 v[64:65], s[18:19], s16, v64, 0
	v_cvt_pk_bf16_f32 v44, v44, v45
	v_cvt_pk_bf16_f32 v45, v46, v47
	v_cvt_pk_bf16_f32 v46, v40, v41
	v_add_u32_e32 v40, 0x90, v146
	global_store_dwordx4 v[108:109], v[104:107], off
	v_cvt_pk_bf16_f32 v88, v100, v101
	v_cvt_pk_bf16_f32 v89, v102, v103
	v_cvt_pk_bf16_f32 v90, v96, v97
	v_cvt_pk_bf16_f32 v91, v98, v99
	global_store_dwordx4 v[92:93], v[76:79], off offset:256
	v_cvt_pk_bf16_f32 v74, v80, v81
	v_cvt_pk_bf16_f32 v75, v82, v83
	v_lshl_add_u64 v[76:77], v[72:73], 1, v[142:143]
	v_cvt_pk_bf16_f32 v72, v84, v85
	v_cvt_pk_bf16_f32 v73, v86, v87
	v_cvt_pk_bf16_f32 v71, v66, v67
	v_lshl_add_u64 v[64:65], v[64:65], 1, v[142:143]
	v_cvt_pk_bf16_f32 v47, v42, v43
	v_mad_i64_i32 v[40:41], s[18:19], s16, v40, 0
	v_cvt_pk_bf16_f32 v28, v28, v29
	v_cvt_pk_bf16_f32 v29, v30, v31
	v_cvt_pk_bf16_f32 v30, v24, v25
	v_add_u32_e32 v24, 0xa0, v146
	global_store_dwordx4 v[92:93], v[88:91], off
	global_store_dwordx4 v[76:77], v[72:75], off
	global_store_dwordx4 v[76:77], v[68:71], off offset:256
	v_cvt_pk_bf16_f32 v60, v60, v61
	v_cvt_pk_bf16_f32 v61, v62, v63
	v_cvt_pk_bf16_f32 v62, v56, v57
	v_cvt_pk_bf16_f32 v63, v58, v59
	global_store_dwordx4 v[64:65], v[44:47], off offset:256
	v_cvt_pk_bf16_f32 v31, v26, v27
	v_mad_i64_i32 v[24:25], s[18:19], s16, v24, 0
	v_lshl_add_u64 v[44:45], v[40:41], 1, v[142:143]
	v_cvt_pk_bf16_f32 v12, v12, v13
	v_cvt_pk_bf16_f32 v13, v14, v15
	v_cvt_pk_bf16_f32 v14, v8, v9
	v_add_u32_e32 v8, 0xb0, v146
	global_store_dwordx4 v[64:65], v[60:63], off
	v_cvt_pk_bf16_f32 v40, v52, v53
	v_cvt_pk_bf16_f32 v41, v54, v55
	v_cvt_pk_bf16_f32 v42, v48, v49
	v_cvt_pk_bf16_f32 v43, v50, v51
	global_store_dwordx4 v[44:45], v[28:31], off offset:256
	v_cvt_pk_bf16_f32 v15, v10, v11
	v_mad_i64_i32 v[8:9], s[16:17], s16, v8, 0
	v_lshl_add_u64 v[28:29], v[24:25], 1, v[142:143]
	global_store_dwordx4 v[44:45], v[40:43], off
	v_cvt_pk_bf16_f32 v24, v36, v37
	v_cvt_pk_bf16_f32 v25, v38, v39
	v_cvt_pk_bf16_f32 v26, v32, v33
	v_cvt_pk_bf16_f32 v27, v34, v35
	global_store_dwordx4 v[28:29], v[12:15], off offset:256
	v_cvt_pk_bf16_f32 v10, v16, v17
	v_cvt_pk_bf16_f32 v11, v18, v19
	v_lshl_add_u64 v[12:13], v[8:9], 1, v[142:143]
	v_cvt_pk_bf16_f32 v8, v20, v21
	v_cvt_pk_bf16_f32 v9, v22, v23
	v_cvt_pk_bf16_f32 v4, v4, v5
	v_cvt_pk_bf16_f32 v5, v6, v7
	v_cvt_pk_bf16_f32 v6, v0, v1
	v_cvt_pk_bf16_f32 v7, v2, v3
	s_and_b64 vcc, exec, s[4:5]
	s_mov_b64 s[4:5], -1
	global_store_dwordx4 v[28:29], v[24:27], off
	global_store_dwordx4 v[12:13], v[8:11], off
	global_store_dwordx4 v[12:13], v[4:7], off offset:256
	s_cbranch_vccnz .LBB0_346
	s_andn2_b64 vcc, exec, s[6:7]
	s_cbranch_vccnz .LBB0_345
	s_branch .LBB0_345
.LBB0_361:
	s_waitcnt vmcnt(0)
	s_and_b64 vcc, exec, s[8:9]
	s_cbranch_vccz .Lunal_361
	s_barrier
.Lunal_361:
	s_barrier
.LBB0_362:
	s_mov_b64 s[4:5], 0
